# v050 + the two closing waits of every K-loop load segment merged into one s_waitcnt vmcnt(8) lgkmcnt(0)
# baseline (speedup 1.0000x reference)
.LBB0_270:
	s_add_u32 s34, s8, 0xfff80080
	s_addc_u32 s35, s9, -1
	s_and_b64 s[30:31], s[30:31], exec
	s_cselect_b32 s35, s2, s35
	s_cselect_b32 s34, s25, s34
	s_cselect_b32 s31, s23, s55
	s_cselect_b32 s30, s54, s1
	s_add_i32 s57, 0, 0x10000
	v_add_u32_e32 v72, s57, v181
	s_add_i32 s62, 0, 0x14000
	ds_read_b128 v[68:71], v72
	ds_read_b128 v[82:85], v72 offset:1024
	ds_read_b128 v[86:89], v72 offset:2048
	ds_read_b128 v[146:149], v72 offset:3072
	v_add_u32_e32 v72, s62, v181
	ds_read_b128 v[150:153], v72
	ds_read_b128 v[154:157], v72 offset:1024
	ds_read_b128 v[158:161], v72 offset:2048
	ds_read_b128 v[202:205], v72 offset:3072
	v_lshl_add_u64 v[72:73], s[8:9], 0, v[172:173]
	s_add_i32 m0, s41, 0xc000
	ds_read_b128 v[206:209], v199
	ds_read_b128 v[210:213], v199 offset:1024
	ds_read_b128 v[214:217], v199 offset:2048
	ds_read_b128 v[226:229], v199 offset:3072
	ds_read_b128 v[230:233], v199 offset:4096
	ds_read_b128 v[234:237], v199 offset:5120
	ds_read_b128 v[238:241], v199 offset:6144
	ds_read_b128 v[242:245], v199 offset:7168
	global_load_lds_dwordx4 v[72:73], off
	v_lshl_add_u64 v[72:73], s[8:9], 0, v[170:171]
	s_add_i32 m0, s41, 0xe000
	s_nop 0
	global_load_lds_dwordx4 v[72:73], off
	s_waitcnt vmcnt(8) lgkmcnt(0)
	s_barrier
	s_setprio 1
	v_mfma_f32_16x16x32_bf16 v[142:145], v[68:71], v[206:209], v[142:145]
	v_mfma_f32_16x16x32_bf16 v[138:141], v[86:89], v[206:209], v[138:141]
	v_mfma_f32_16x16x32_bf16 v[126:129], v[68:71], v[214:217], v[126:129]
	v_mfma_f32_16x16x32_bf16 v[122:125], v[86:89], v[214:217], v[122:125]
	v_mfma_f32_16x16x32_bf16 v[110:113], v[68:71], v[230:233], v[110:113]
	v_mfma_f32_16x16x32_bf16 v[106:109], v[86:89], v[230:233], v[106:109]
	v_mfma_f32_16x16x32_bf16 v[94:97], v[68:71], v[238:241], v[94:97]
	v_mfma_f32_16x16x32_bf16 v[90:93], v[86:89], v[238:241], v[90:93]
	v_mfma_f32_16x16x32_bf16 v[142:145], v[82:85], v[210:213], v[142:145]
	v_mfma_f32_16x16x32_bf16 v[138:141], v[146:149], v[210:213], v[138:141]
	v_mfma_f32_16x16x32_bf16 v[126:129], v[82:85], v[226:229], v[126:129]
	v_mfma_f32_16x16x32_bf16 v[122:125], v[146:149], v[226:229], v[122:125]
	v_mfma_f32_16x16x32_bf16 v[110:113], v[82:85], v[234:237], v[110:113]
	v_mfma_f32_16x16x32_bf16 v[106:109], v[146:149], v[234:237], v[106:109]
	v_mfma_f32_16x16x32_bf16 v[94:97], v[82:85], v[242:245], v[94:97]
	v_mfma_f32_16x16x32_bf16 v[90:93], v[146:149], v[242:245], v[90:93]
	v_mfma_f32_16x16x32_bf16 v[134:137], v[150:153], v[206:209], v[134:137]
	v_mfma_f32_16x16x32_bf16 v[130:133], v[158:161], v[206:209], v[130:133]
	v_mfma_f32_16x16x32_bf16 v[118:121], v[150:153], v[214:217], v[118:121]
	v_mfma_f32_16x16x32_bf16 v[114:117], v[158:161], v[214:217], v[114:117]
	v_mfma_f32_16x16x32_bf16 v[102:105], v[150:153], v[230:233], v[102:105]
	v_mfma_f32_16x16x32_bf16 v[98:101], v[158:161], v[230:233], v[98:101]
	v_mfma_f32_16x16x32_bf16 v[78:81], v[150:153], v[238:241], v[78:81]
	v_mfma_f32_16x16x32_bf16 v[72:75], v[158:161], v[238:241], v[74:77]
	v_mfma_f32_16x16x32_bf16 v[134:137], v[154:157], v[210:213], v[134:137]
	v_mfma_f32_16x16x32_bf16 v[130:133], v[202:205], v[210:213], v[130:133]
	v_mfma_f32_16x16x32_bf16 v[118:121], v[154:157], v[226:229], v[118:121]
	v_mfma_f32_16x16x32_bf16 v[114:117], v[202:205], v[226:229], v[114:117]
	v_mfma_f32_16x16x32_bf16 v[102:105], v[154:157], v[234:237], v[102:105]
	v_mfma_f32_16x16x32_bf16 v[98:101], v[202:205], v[234:237], v[98:101]
	v_mfma_f32_16x16x32_bf16 v[78:81], v[154:157], v[242:245], v[78:81]
	v_mfma_f32_16x16x32_bf16 v[72:75], v[202:205], v[242:245], v[72:75]
	s_setprio 0
	s_barrier
	s_add_i32 s57, s57, s40
	v_lshl_add_u64 v[178:179], s[30:31], 0, v[0:1]
	s_mov_b32 m0, s57
	ds_read_b128 v[206:209], v199 offset:16384
	ds_read_b128 v[210:213], v199 offset:17408
	ds_read_b128 v[214:217], v199 offset:18432
	ds_read_b128 v[226:229], v199 offset:19456
	ds_read_b128 v[230:233], v199 offset:20480
	ds_read_b128 v[234:237], v199 offset:21504
	ds_read_b128 v[238:241], v199 offset:22528
	ds_read_b128 v[242:245], v199 offset:23552
	global_load_lds_dwordx4 v[178:179], off
	s_add_i32 m0, s57, 0x2000
	s_add_u32 s60, s30, 0x80000
	v_lshl_add_u64 v[250:251], s[30:31], 0, v[162:163]
	s_addc_u32 s61, s31, 0
	s_add_i32 s57, s62, s40
	global_load_lds_dwordx4 v[250:251], off
	v_lshl_add_u64 v[76:77], s[60:61], 0, v[0:1]
	s_mov_b32 m0, s57
	v_lshl_add_u64 v[252:253], s[34:35], 0, v[166:167]
	global_load_lds_dwordx4 v[76:77], off
	v_lshl_add_u64 v[76:77], s[60:61], 0, v[162:163]
	s_add_i32 m0, s57, 0x2000
	v_lshl_add_u64 v[220:221], s[34:35], 0, v[164:165]
	global_load_lds_dwordx4 v[76:77], off
	s_mov_b32 m0, s41
	s_nop 0
	global_load_lds_dwordx4 v[252:253], off
	s_mov_b32 m0, s42
	s_nop 0
	global_load_lds_dwordx4 v[220:221], off
	s_waitcnt vmcnt(8) lgkmcnt(0)
	s_barrier
	s_setprio 1
	v_mfma_f32_16x16x32_bf16 v[62:65], v[68:71], v[206:209], v[62:65]
	v_mfma_f32_16x16x32_bf16 v[58:61], v[86:89], v[206:209], v[58:61]
	v_mfma_f32_16x16x32_bf16 v[46:49], v[68:71], v[214:217], v[46:49]
	v_mfma_f32_16x16x32_bf16 v[42:45], v[86:89], v[214:217], v[42:45]
	v_mfma_f32_16x16x32_bf16 v[30:33], v[68:71], v[230:233], v[30:33]
	v_mfma_f32_16x16x32_bf16 v[26:29], v[86:89], v[230:233], v[26:29]
	v_mfma_f32_16x16x32_bf16 v[14:17], v[68:71], v[238:241], v[14:17]
	v_mfma_f32_16x16x32_bf16 v[10:13], v[86:89], v[238:241], v[10:13]
	v_mfma_f32_16x16x32_bf16 v[62:65], v[82:85], v[210:213], v[62:65]
	v_mfma_f32_16x16x32_bf16 v[58:61], v[146:149], v[210:213], v[58:61]
	v_mfma_f32_16x16x32_bf16 v[46:49], v[82:85], v[226:229], v[46:49]
	v_mfma_f32_16x16x32_bf16 v[42:45], v[146:149], v[226:229], v[42:45]
	v_mfma_f32_16x16x32_bf16 v[30:33], v[82:85], v[234:237], v[30:33]
	v_mfma_f32_16x16x32_bf16 v[26:29], v[146:149], v[234:237], v[26:29]
	v_mfma_f32_16x16x32_bf16 v[14:17], v[82:85], v[242:245], v[14:17]
	v_mfma_f32_16x16x32_bf16 v[10:13], v[146:149], v[242:245], v[10:13]
	v_mfma_f32_16x16x32_bf16 v[54:57], v[150:153], v[206:209], v[54:57]
	v_mfma_f32_16x16x32_bf16 v[50:53], v[158:161], v[206:209], v[50:53]
	v_mfma_f32_16x16x32_bf16 v[38:41], v[150:153], v[214:217], v[38:41]
	v_mfma_f32_16x16x32_bf16 v[34:37], v[158:161], v[214:217], v[34:37]
	v_mfma_f32_16x16x32_bf16 v[22:25], v[150:153], v[230:233], v[22:25]
	v_mfma_f32_16x16x32_bf16 v[18:21], v[158:161], v[230:233], v[18:21]
	v_mfma_f32_16x16x32_bf16 v[6:9], v[150:153], v[238:241], v[6:9]
	v_mfma_f32_16x16x32_bf16 v[2:5], v[158:161], v[238:241], v[2:5]
	v_mfma_f32_16x16x32_bf16 v[54:57], v[154:157], v[210:213], v[54:57]
	v_mfma_f32_16x16x32_bf16 v[50:53], v[202:205], v[210:213], v[50:53]
	v_mfma_f32_16x16x32_bf16 v[38:41], v[154:157], v[226:229], v[38:41]
	v_mfma_f32_16x16x32_bf16 v[34:37], v[202:205], v[226:229], v[34:37]
	v_mfma_f32_16x16x32_bf16 v[22:25], v[154:157], v[234:237], v[22:25]
	v_mfma_f32_16x16x32_bf16 v[18:21], v[202:205], v[234:237], v[18:21]
	v_mfma_f32_16x16x32_bf16 v[6:9], v[154:157], v[242:245], v[6:9]
	v_mfma_f32_16x16x32_bf16 v[2:5], v[202:205], v[242:245], v[2:5]
	s_setprio 0
	s_barrier
	s_add_i32 s57, 0, 0x18000
	v_add_u32_e32 v76, s57, v181
	s_add_i32 s60, 0, 0x1c000
	ds_read_b128 v[68:71], v76
	ds_read_b128 v[82:85], v76 offset:1024
	ds_read_b128 v[86:89], v76 offset:2048
	ds_read_b128 v[146:149], v76 offset:3072
	v_add_u32_e32 v76, s60, v181
	ds_read_b128 v[150:153], v76
	ds_read_b128 v[154:157], v76 offset:1024
	ds_read_b128 v[158:161], v76 offset:2048
	ds_read_b128 v[202:205], v76 offset:3072
	s_add_u32 s34, s34, 0x80000
	s_addc_u32 s35, s35, 0
	s_mov_b32 m0, s43
	v_lshl_add_u64 v[76:77], s[34:35], 0, v[166:167]
	ds_read_b128 v[206:209], v199 offset:32768
	ds_read_b128 v[210:213], v199 offset:33792
	ds_read_b128 v[214:217], v199 offset:34816
	ds_read_b128 v[226:229], v199 offset:35840
	ds_read_b128 v[230:233], v199 offset:36864
	ds_read_b128 v[234:237], v199 offset:37888
	ds_read_b128 v[238:241], v199 offset:38912
	ds_read_b128 v[242:245], v199 offset:39936
	global_load_lds_dwordx4 v[76:77], off
	v_lshl_add_u64 v[76:77], s[34:35], 0, v[164:165]
	s_mov_b32 m0, s44
	s_nop 0
	global_load_lds_dwordx4 v[76:77], off
	s_waitcnt vmcnt(8) lgkmcnt(0)
	s_barrier
	s_setprio 1
	v_mfma_f32_16x16x32_bf16 v[142:145], v[68:71], v[206:209], v[142:145]
	v_mfma_f32_16x16x32_bf16 v[138:141], v[86:89], v[206:209], v[138:141]
	v_mfma_f32_16x16x32_bf16 v[126:129], v[68:71], v[214:217], v[126:129]
	v_mfma_f32_16x16x32_bf16 v[122:125], v[86:89], v[214:217], v[122:125]
	v_mfma_f32_16x16x32_bf16 v[110:113], v[68:71], v[230:233], v[110:113]
	v_mfma_f32_16x16x32_bf16 v[106:109], v[86:89], v[230:233], v[106:109]
	v_mfma_f32_16x16x32_bf16 v[94:97], v[68:71], v[238:241], v[94:97]
	v_mfma_f32_16x16x32_bf16 v[90:93], v[86:89], v[238:241], v[90:93]
	v_mfma_f32_16x16x32_bf16 v[142:145], v[82:85], v[210:213], v[142:145]
	v_mfma_f32_16x16x32_bf16 v[138:141], v[146:149], v[210:213], v[138:141]
	v_mfma_f32_16x16x32_bf16 v[126:129], v[82:85], v[226:229], v[126:129]
	v_mfma_f32_16x16x32_bf16 v[122:125], v[146:149], v[226:229], v[122:125]
	v_mfma_f32_16x16x32_bf16 v[110:113], v[82:85], v[234:237], v[110:113]
	v_mfma_f32_16x16x32_bf16 v[106:109], v[146:149], v[234:237], v[106:109]
	v_mfma_f32_16x16x32_bf16 v[94:97], v[82:85], v[242:245], v[94:97]
	v_mfma_f32_16x16x32_bf16 v[90:93], v[146:149], v[242:245], v[90:93]
	v_mfma_f32_16x16x32_bf16 v[134:137], v[150:153], v[206:209], v[134:137]
	v_mfma_f32_16x16x32_bf16 v[130:133], v[158:161], v[206:209], v[130:133]
	v_mfma_f32_16x16x32_bf16 v[118:121], v[150:153], v[214:217], v[118:121]
	v_mfma_f32_16x16x32_bf16 v[114:117], v[158:161], v[214:217], v[114:117]
	v_mfma_f32_16x16x32_bf16 v[102:105], v[150:153], v[230:233], v[102:105]
	v_mfma_f32_16x16x32_bf16 v[98:101], v[158:161], v[230:233], v[98:101]
	v_mfma_f32_16x16x32_bf16 v[76:79], v[150:153], v[238:241], v[78:81]
	v_mfma_f32_16x16x32_bf16 v[72:75], v[158:161], v[238:241], v[72:75]
	v_mfma_f32_16x16x32_bf16 v[134:137], v[154:157], v[210:213], v[134:137]
	v_mfma_f32_16x16x32_bf16 v[130:133], v[202:205], v[210:213], v[130:133]
	v_mfma_f32_16x16x32_bf16 v[118:121], v[154:157], v[226:229], v[118:121]
	v_mfma_f32_16x16x32_bf16 v[114:117], v[202:205], v[226:229], v[114:117]
	v_mfma_f32_16x16x32_bf16 v[102:105], v[154:157], v[234:237], v[102:105]
	v_mfma_f32_16x16x32_bf16 v[98:101], v[202:205], v[234:237], v[98:101]
	v_mfma_f32_16x16x32_bf16 v[78:81], v[154:157], v[242:245], v[76:79]
	v_mfma_f32_16x16x32_bf16 v[74:77], v[202:205], v[242:245], v[72:75]
	s_setprio 0
	s_barrier
	s_add_i32 s34, s57, s40
	v_lshl_add_u64 v[72:73], v[178:179], 0, s[96:97]
	s_mov_b32 m0, s34
	ds_read_b128 v[206:209], v199 offset:49152
	ds_read_b128 v[210:213], v199 offset:50176
	ds_read_b128 v[214:217], v199 offset:51200
	ds_read_b128 v[226:229], v199 offset:52224
	ds_read_b128 v[230:233], v199 offset:53248
	ds_read_b128 v[234:237], v199 offset:54272
	ds_read_b128 v[238:241], v199 offset:55296
	ds_read_b128 v[242:245], v199 offset:56320
	global_load_lds_dwordx4 v[72:73], off
	s_add_i32 m0, s34, 0x2000
	s_add_u32 s30, s30, 0x80080
	v_lshl_add_u64 v[72:73], v[250:251], 0, s[96:97]
	s_addc_u32 s31, s31, 0
	s_add_i32 s34, s60, s40
	global_load_lds_dwordx4 v[72:73], off
	v_lshl_add_u64 v[72:73], s[30:31], 0, v[0:1]
	s_mov_b32 m0, s34
	s_nop 0
	global_load_lds_dwordx4 v[72:73], off
	v_lshl_add_u64 v[72:73], s[30:31], 0, v[162:163]
	s_add_i32 m0, s34, 0x2000
	s_nop 0
	global_load_lds_dwordx4 v[72:73], off
	v_lshl_add_u64 v[72:73], v[252:253], 0, s[96:97]
	s_mov_b32 m0, s47
	s_nop 0
	global_load_lds_dwordx4 v[72:73], off
	v_lshl_add_u64 v[72:73], v[220:221], 0, s[96:97]
	s_mov_b32 m0, s50
	s_nop 0
	global_load_lds_dwordx4 v[72:73], off
	s_waitcnt vmcnt(8) lgkmcnt(0)
	s_barrier
	s_setprio 1
	v_mfma_f32_16x16x32_bf16 v[62:65], v[68:71], v[206:209], v[62:65]
	v_mfma_f32_16x16x32_bf16 v[58:61], v[86:89], v[206:209], v[58:61]
	v_mfma_f32_16x16x32_bf16 v[46:49], v[68:71], v[214:217], v[46:49]
	v_mfma_f32_16x16x32_bf16 v[42:45], v[86:89], v[214:217], v[42:45]
	v_mfma_f32_16x16x32_bf16 v[30:33], v[68:71], v[230:233], v[30:33]
	v_mfma_f32_16x16x32_bf16 v[26:29], v[86:89], v[230:233], v[26:29]
	v_mfma_f32_16x16x32_bf16 v[14:17], v[68:71], v[238:241], v[14:17]
	v_mfma_f32_16x16x32_bf16 v[10:13], v[86:89], v[238:241], v[10:13]
	v_mfma_f32_16x16x32_bf16 v[62:65], v[82:85], v[210:213], v[62:65]
	v_mfma_f32_16x16x32_bf16 v[58:61], v[146:149], v[210:213], v[58:61]
	v_mfma_f32_16x16x32_bf16 v[46:49], v[82:85], v[226:229], v[46:49]
	v_mfma_f32_16x16x32_bf16 v[42:45], v[146:149], v[226:229], v[42:45]
	v_mfma_f32_16x16x32_bf16 v[30:33], v[82:85], v[234:237], v[30:33]
	v_mfma_f32_16x16x32_bf16 v[26:29], v[146:149], v[234:237], v[26:29]
	v_mfma_f32_16x16x32_bf16 v[14:17], v[82:85], v[242:245], v[14:17]
	v_mfma_f32_16x16x32_bf16 v[10:13], v[146:149], v[242:245], v[10:13]
	v_mfma_f32_16x16x32_bf16 v[54:57], v[150:153], v[206:209], v[54:57]
	v_mfma_f32_16x16x32_bf16 v[50:53], v[158:161], v[206:209], v[50:53]
	v_mfma_f32_16x16x32_bf16 v[38:41], v[150:153], v[214:217], v[38:41]
	v_mfma_f32_16x16x32_bf16 v[34:37], v[158:161], v[214:217], v[34:37]
	v_mfma_f32_16x16x32_bf16 v[22:25], v[150:153], v[230:233], v[22:25]
	v_mfma_f32_16x16x32_bf16 v[18:21], v[158:161], v[230:233], v[18:21]
	v_mfma_f32_16x16x32_bf16 v[6:9], v[150:153], v[238:241], v[6:9]
	v_mfma_f32_16x16x32_bf16 v[2:5], v[158:161], v[238:241], v[2:5]
	v_mfma_f32_16x16x32_bf16 v[54:57], v[154:157], v[210:213], v[54:57]
	v_mfma_f32_16x16x32_bf16 v[50:53], v[202:205], v[210:213], v[50:53]
	v_mfma_f32_16x16x32_bf16 v[38:41], v[154:157], v[226:229], v[38:41]
	v_mfma_f32_16x16x32_bf16 v[34:37], v[202:205], v[226:229], v[34:37]
	v_mfma_f32_16x16x32_bf16 v[22:25], v[154:157], v[234:237], v[22:25]
	v_mfma_f32_16x16x32_bf16 v[18:21], v[202:205], v[234:237], v[18:21]
	v_mfma_f32_16x16x32_bf16 v[6:9], v[154:157], v[242:245], v[6:9]
	v_mfma_f32_16x16x32_bf16 v[2:5], v[202:205], v[242:245], v[2:5]
	s_setprio 0
	s_barrier
	s_add_i32 s56, s56, 2
	s_add_u32 s1, s1, 0x100
	s_addc_u32 s55, s55, 0
	s_add_u32 s8, s8, 0x100
	s_addc_u32 s9, s9, 0
	s_cmp_gt_u32 s56, 29
	s_cbranch_scc1 .LBB0_273

.LBB0_617:
	s_add_u32 s34, s8, 0xfff80080
	s_addc_u32 s35, s9, -1
	s_add_i32 s64, 0, 0x10000
	s_cmp_eq_u32 s63, 28
	s_cselect_b32 s37, s21, s35
	s_cselect_b32 s36, s23, s34
	v_add_u32_e32 v0, s64, v212
	s_cselect_b32 s35, s25, s62
	s_cselect_b32 s34, s27, s61
	s_add_i32 s66, 0, 0x14000
	ds_read_b128 v[66:69], v0
	ds_read_b128 v[70:73], v0 offset:1024
	ds_read_b128 v[74:77], v0 offset:2048
	ds_read_b128 v[78:81], v0 offset:3072
	v_add_u32_e32 v0, s66, v212
	ds_read_b128 v[130:133], v0
	ds_read_b128 v[142:145], v0 offset:1024
	ds_read_b128 v[146:149], v0 offset:2048
	ds_read_b128 v[158:161], v0 offset:3072
	v_lshl_add_u64 v[220:221], s[8:9], 0, v[190:191]
	s_add_i32 m0, s42, 0xc000
	ds_read_b128 v[162:165], v215
	ds_read_b128 v[166:169], v215 offset:1024
	ds_read_b128 v[170:173], v215 offset:2048
	ds_read_b128 v[192:195], v215 offset:3072
	ds_read_b128 v[196:199], v215 offset:4096
	ds_read_b128 v[200:203], v215 offset:5120
	ds_read_b128 v[204:207], v215 offset:6144
	ds_read_b128 v[208:211], v215 offset:7168
	global_load_lds_dwordx4 v[220:221], off
	v_lshl_add_u64 v[220:221], s[8:9], 0, v[188:189]
	s_add_i32 m0, s42, 0xe000
	s_nop 0
	global_load_lds_dwordx4 v[220:221], off
	s_waitcnt vmcnt(8) lgkmcnt(0)
	s_barrier
	s_setprio 1
	v_mfma_f32_16x16x32_bf16 v[154:157], v[66:69], v[162:165], v[154:157]
	v_mfma_f32_16x16x32_bf16 v[150:153], v[74:77], v[162:165], v[150:153]
	v_mfma_f32_16x16x32_bf16 v[138:141], v[66:69], v[170:173], v[138:141]
	v_mfma_f32_16x16x32_bf16 v[134:137], v[74:77], v[170:173], v[134:137]
	v_mfma_f32_16x16x32_bf16 v[110:113], v[66:69], v[196:199], v[110:113]
	v_mfma_f32_16x16x32_bf16 v[106:109], v[74:77], v[196:199], v[106:109]
	v_mfma_f32_16x16x32_bf16 v[94:97], v[66:69], v[204:207], v[94:97]
	v_mfma_f32_16x16x32_bf16 v[90:93], v[74:77], v[204:207], v[90:93]
	v_mfma_f32_16x16x32_bf16 v[154:157], v[70:73], v[166:169], v[154:157]
	v_mfma_f32_16x16x32_bf16 v[150:153], v[78:81], v[166:169], v[150:153]
	v_mfma_f32_16x16x32_bf16 v[138:141], v[70:73], v[192:195], v[138:141]
	v_mfma_f32_16x16x32_bf16 v[134:137], v[78:81], v[192:195], v[134:137]
	v_mfma_f32_16x16x32_bf16 v[110:113], v[70:73], v[200:203], v[110:113]
	v_mfma_f32_16x16x32_bf16 v[106:109], v[78:81], v[200:203], v[106:109]
	v_mfma_f32_16x16x32_bf16 v[94:97], v[70:73], v[208:211], v[94:97]
	v_mfma_f32_16x16x32_bf16 v[90:93], v[78:81], v[208:211], v[90:93]
	v_mfma_f32_16x16x32_bf16 v[126:129], v[130:133], v[162:165], v[126:129]
	v_mfma_f32_16x16x32_bf16 v[114:117], v[146:149], v[162:165], v[114:117]
	v_mfma_f32_16x16x32_bf16 v[122:125], v[130:133], v[170:173], v[122:125]
	v_mfma_f32_16x16x32_bf16 v[118:121], v[146:149], v[170:173], v[118:121]
	v_mfma_f32_16x16x32_bf16 v[102:105], v[130:133], v[196:199], v[102:105]
	v_mfma_f32_16x16x32_bf16 v[98:101], v[146:149], v[196:199], v[98:101]
	v_mfma_f32_16x16x32_bf16 v[86:89], v[130:133], v[204:207], v[86:89]
	v_mfma_f32_16x16x32_bf16 v[82:85], v[146:149], v[204:207], v[82:85]
	v_mfma_f32_16x16x32_bf16 v[126:129], v[142:145], v[166:169], v[126:129]
	v_mfma_f32_16x16x32_bf16 v[114:117], v[158:161], v[166:169], v[114:117]
	v_mfma_f32_16x16x32_bf16 v[122:125], v[142:145], v[192:195], v[122:125]
	v_mfma_f32_16x16x32_bf16 v[118:121], v[158:161], v[192:195], v[118:121]
	v_mfma_f32_16x16x32_bf16 v[102:105], v[142:145], v[200:203], v[102:105]
	v_mfma_f32_16x16x32_bf16 v[98:101], v[158:161], v[200:203], v[98:101]
	v_mfma_f32_16x16x32_bf16 v[86:89], v[142:145], v[208:211], v[86:89]
	v_mfma_f32_16x16x32_bf16 v[82:85], v[158:161], v[208:211], v[82:85]
	s_setprio 0
	s_barrier
	s_add_i32 s64, s64, s41
	v_lshl_add_u64 v[220:221], s[34:35], 0, v[182:183]
	s_mov_b32 m0, s64
	ds_read_b128 v[162:165], v215 offset:16384
	ds_read_b128 v[166:169], v215 offset:17408
	ds_read_b128 v[170:173], v215 offset:18432
	ds_read_b128 v[192:195], v215 offset:19456
	ds_read_b128 v[196:199], v215 offset:20480
	ds_read_b128 v[200:203], v215 offset:21504
	ds_read_b128 v[204:207], v215 offset:22528
	ds_read_b128 v[208:211], v215 offset:23552
	global_load_lds_dwordx4 v[220:221], off
	s_add_i32 m0, s64, 0x2000
	s_add_u32 s64, s34, 0x80000
	v_lshl_add_u64 v[230:231], s[34:35], 0, v[178:179]
	s_addc_u32 s65, s35, 0
	s_add_i32 s66, s66, s41
	global_load_lds_dwordx4 v[230:231], off
	v_lshl_add_u64 v[232:233], s[64:65], 0, v[182:183]
	s_mov_b32 m0, s66
	v_lshl_add_u64 v[234:235], s[36:37], 0, v[180:181]
	global_load_lds_dwordx4 v[232:233], off
	v_lshl_add_u64 v[232:233], s[64:65], 0, v[178:179]
	s_add_i32 m0, s66, 0x2000
	s_nop 0
	global_load_lds_dwordx4 v[232:233], off
	v_lshl_add_u64 v[232:233], s[36:37], 0, v[184:185]
	s_mov_b32 m0, s42
	s_nop 0
	global_load_lds_dwordx4 v[232:233], off
	s_mov_b32 m0, s43
	s_nop 0
	global_load_lds_dwordx4 v[234:235], off
	s_waitcnt vmcnt(8) lgkmcnt(0)
	s_barrier
	s_setprio 1
	v_mfma_f32_16x16x32_bf16 v[62:65], v[66:69], v[162:165], v[62:65]
	v_mfma_f32_16x16x32_bf16 v[58:61], v[74:77], v[162:165], v[58:61]
	v_mfma_f32_16x16x32_bf16 v[46:49], v[66:69], v[170:173], v[46:49]
	v_mfma_f32_16x16x32_bf16 v[42:45], v[74:77], v[170:173], v[42:45]
	v_mfma_f32_16x16x32_bf16 v[30:33], v[66:69], v[196:199], v[30:33]
	v_mfma_f32_16x16x32_bf16 v[26:29], v[74:77], v[196:199], v[26:29]
	v_mfma_f32_16x16x32_bf16 v[14:17], v[66:69], v[204:207], v[14:17]
	v_mfma_f32_16x16x32_bf16 v[10:13], v[74:77], v[204:207], v[10:13]
	v_mfma_f32_16x16x32_bf16 v[62:65], v[70:73], v[166:169], v[62:65]
	v_mfma_f32_16x16x32_bf16 v[58:61], v[78:81], v[166:169], v[58:61]
	v_mfma_f32_16x16x32_bf16 v[46:49], v[70:73], v[192:195], v[46:49]
	v_mfma_f32_16x16x32_bf16 v[42:45], v[78:81], v[192:195], v[42:45]
	v_mfma_f32_16x16x32_bf16 v[30:33], v[70:73], v[200:203], v[30:33]
	v_mfma_f32_16x16x32_bf16 v[26:29], v[78:81], v[200:203], v[26:29]
	v_mfma_f32_16x16x32_bf16 v[14:17], v[70:73], v[208:211], v[14:17]
	v_mfma_f32_16x16x32_bf16 v[10:13], v[78:81], v[208:211], v[10:13]
	v_mfma_f32_16x16x32_bf16 v[54:57], v[130:133], v[162:165], v[54:57]
	v_mfma_f32_16x16x32_bf16 v[50:53], v[146:149], v[162:165], v[50:53]
	v_mfma_f32_16x16x32_bf16 v[38:41], v[130:133], v[170:173], v[38:41]
	v_mfma_f32_16x16x32_bf16 v[34:37], v[146:149], v[170:173], v[34:37]
	v_mfma_f32_16x16x32_bf16 v[22:25], v[130:133], v[196:199], v[22:25]
	v_mfma_f32_16x16x32_bf16 v[18:21], v[146:149], v[196:199], v[18:21]
	v_mfma_f32_16x16x32_bf16 v[6:9], v[130:133], v[204:207], v[6:9]
	v_mfma_f32_16x16x32_bf16 v[2:5], v[146:149], v[204:207], v[2:5]
	v_mfma_f32_16x16x32_bf16 v[54:57], v[142:145], v[166:169], v[54:57]
	v_mfma_f32_16x16x32_bf16 v[50:53], v[158:161], v[166:169], v[50:53]
	v_mfma_f32_16x16x32_bf16 v[38:41], v[142:145], v[192:195], v[38:41]
	v_mfma_f32_16x16x32_bf16 v[34:37], v[158:161], v[192:195], v[34:37]
	v_mfma_f32_16x16x32_bf16 v[22:25], v[142:145], v[200:203], v[22:25]
	v_mfma_f32_16x16x32_bf16 v[18:21], v[158:161], v[200:203], v[18:21]
	v_mfma_f32_16x16x32_bf16 v[6:9], v[142:145], v[208:211], v[6:9]
	v_mfma_f32_16x16x32_bf16 v[2:5], v[158:161], v[208:211], v[2:5]
	s_setprio 0
	s_barrier
	s_add_i32 s64, 0, 0x18000
	v_add_u32_e32 v0, s64, v212
	s_add_i32 s65, 0, 0x1c000
	ds_read_b128 v[66:69], v0
	ds_read_b128 v[70:73], v0 offset:1024
	ds_read_b128 v[74:77], v0 offset:2048
	ds_read_b128 v[78:81], v0 offset:3072
	v_add_u32_e32 v0, s65, v212
	ds_read_b128 v[130:133], v0
	ds_read_b128 v[142:145], v0 offset:1024
	ds_read_b128 v[146:149], v0 offset:2048
	ds_read_b128 v[158:161], v0 offset:3072
	s_add_u32 s36, s36, 0x80000
	s_addc_u32 s37, s37, 0
	s_mov_b32 m0, s44
	v_lshl_add_u64 v[236:237], s[36:37], 0, v[184:185]
	ds_read_b128 v[162:165], v215 offset:32768
	ds_read_b128 v[166:169], v215 offset:33792
	ds_read_b128 v[170:173], v215 offset:34816
	ds_read_b128 v[192:195], v215 offset:35840
	ds_read_b128 v[196:199], v215 offset:36864
	ds_read_b128 v[200:203], v215 offset:37888
	ds_read_b128 v[204:207], v215 offset:38912
	ds_read_b128 v[208:211], v215 offset:39936
	global_load_lds_dwordx4 v[236:237], off
	v_lshl_add_u64 v[236:237], s[36:37], 0, v[180:181]
	s_mov_b32 m0, s45
	s_nop 0
	global_load_lds_dwordx4 v[236:237], off
	s_waitcnt vmcnt(8) lgkmcnt(0)
	s_barrier
	s_setprio 1
	v_mfma_f32_16x16x32_bf16 v[154:157], v[66:69], v[162:165], v[154:157]
	v_mfma_f32_16x16x32_bf16 v[150:153], v[74:77], v[162:165], v[150:153]
	v_mfma_f32_16x16x32_bf16 v[138:141], v[66:69], v[170:173], v[138:141]
	v_mfma_f32_16x16x32_bf16 v[134:137], v[74:77], v[170:173], v[134:137]
	v_mfma_f32_16x16x32_bf16 v[110:113], v[66:69], v[196:199], v[110:113]
	v_mfma_f32_16x16x32_bf16 v[106:109], v[74:77], v[196:199], v[106:109]
	v_mfma_f32_16x16x32_bf16 v[94:97], v[66:69], v[204:207], v[94:97]
	v_mfma_f32_16x16x32_bf16 v[90:93], v[74:77], v[204:207], v[90:93]
	v_mfma_f32_16x16x32_bf16 v[154:157], v[70:73], v[166:169], v[154:157]
	v_mfma_f32_16x16x32_bf16 v[150:153], v[78:81], v[166:169], v[150:153]
	v_mfma_f32_16x16x32_bf16 v[138:141], v[70:73], v[192:195], v[138:141]
	v_mfma_f32_16x16x32_bf16 v[134:137], v[78:81], v[192:195], v[134:137]
	v_mfma_f32_16x16x32_bf16 v[110:113], v[70:73], v[200:203], v[110:113]
	v_mfma_f32_16x16x32_bf16 v[106:109], v[78:81], v[200:203], v[106:109]
	v_mfma_f32_16x16x32_bf16 v[94:97], v[70:73], v[208:211], v[94:97]
	v_mfma_f32_16x16x32_bf16 v[90:93], v[78:81], v[208:211], v[90:93]
	v_mfma_f32_16x16x32_bf16 v[126:129], v[130:133], v[162:165], v[126:129]
	v_mfma_f32_16x16x32_bf16 v[114:117], v[146:149], v[162:165], v[114:117]
	v_mfma_f32_16x16x32_bf16 v[122:125], v[130:133], v[170:173], v[122:125]
	v_mfma_f32_16x16x32_bf16 v[118:121], v[146:149], v[170:173], v[118:121]
	v_mfma_f32_16x16x32_bf16 v[102:105], v[130:133], v[196:199], v[102:105]
	v_mfma_f32_16x16x32_bf16 v[98:101], v[146:149], v[196:199], v[98:101]
	v_mfma_f32_16x16x32_bf16 v[86:89], v[130:133], v[204:207], v[86:89]
	v_mfma_f32_16x16x32_bf16 v[82:85], v[146:149], v[204:207], v[82:85]
	v_mfma_f32_16x16x32_bf16 v[126:129], v[142:145], v[166:169], v[126:129]
	v_mfma_f32_16x16x32_bf16 v[114:117], v[158:161], v[166:169], v[114:117]
	v_mfma_f32_16x16x32_bf16 v[122:125], v[142:145], v[192:195], v[122:125]
	v_mfma_f32_16x16x32_bf16 v[118:121], v[158:161], v[192:195], v[118:121]
	v_mfma_f32_16x16x32_bf16 v[102:105], v[142:145], v[200:203], v[102:105]
	v_mfma_f32_16x16x32_bf16 v[98:101], v[158:161], v[200:203], v[98:101]
	v_mfma_f32_16x16x32_bf16 v[86:89], v[142:145], v[208:211], v[86:89]
	v_mfma_f32_16x16x32_bf16 v[82:85], v[158:161], v[208:211], v[82:85]
	s_setprio 0
	s_barrier
	s_add_i32 s36, s64, s41
	v_lshl_add_u64 v[220:221], v[220:221], 0, s[96:97]
	s_mov_b32 m0, s36
	ds_read_b128 v[162:165], v215 offset:49152
	ds_read_b128 v[166:169], v215 offset:50176
	ds_read_b128 v[170:173], v215 offset:51200
	ds_read_b128 v[192:195], v215 offset:52224
	ds_read_b128 v[196:199], v215 offset:53248
	ds_read_b128 v[200:203], v215 offset:54272
	ds_read_b128 v[204:207], v215 offset:55296
	ds_read_b128 v[208:211], v215 offset:56320
	global_load_lds_dwordx4 v[220:221], off
	s_add_i32 m0, s36, 0x2000
	s_add_u32 s34, s34, 0x80080
	v_lshl_add_u64 v[220:221], v[230:231], 0, s[96:97]
	s_addc_u32 s35, s35, 0
	s_add_i32 s36, s65, s41
	global_load_lds_dwordx4 v[220:221], off
	v_lshl_add_u64 v[220:221], s[34:35], 0, v[182:183]
	s_mov_b32 m0, s36
	s_nop 0
	global_load_lds_dwordx4 v[220:221], off
	v_lshl_add_u64 v[220:221], s[34:35], 0, v[178:179]
	s_add_i32 m0, s36, 0x2000
	s_nop 0
	global_load_lds_dwordx4 v[220:221], off
	v_lshl_add_u64 v[220:221], v[232:233], 0, s[96:97]
	s_mov_b32 m0, s56
	s_nop 0
	global_load_lds_dwordx4 v[220:221], off
	v_lshl_add_u64 v[220:221], v[234:235], 0, s[96:97]
	s_mov_b32 m0, s57
	s_nop 0
	global_load_lds_dwordx4 v[220:221], off
	s_waitcnt vmcnt(8) lgkmcnt(0)
	s_barrier
	s_setprio 1
	v_mfma_f32_16x16x32_bf16 v[62:65], v[66:69], v[162:165], v[62:65]
	v_mfma_f32_16x16x32_bf16 v[58:61], v[74:77], v[162:165], v[58:61]
	v_mfma_f32_16x16x32_bf16 v[46:49], v[66:69], v[170:173], v[46:49]
	v_mfma_f32_16x16x32_bf16 v[42:45], v[74:77], v[170:173], v[42:45]
	v_mfma_f32_16x16x32_bf16 v[30:33], v[66:69], v[196:199], v[30:33]
	v_mfma_f32_16x16x32_bf16 v[26:29], v[74:77], v[196:199], v[26:29]
	v_mfma_f32_16x16x32_bf16 v[14:17], v[66:69], v[204:207], v[14:17]
	v_mfma_f32_16x16x32_bf16 v[10:13], v[74:77], v[204:207], v[10:13]
	v_mfma_f32_16x16x32_bf16 v[62:65], v[70:73], v[166:169], v[62:65]
	v_mfma_f32_16x16x32_bf16 v[58:61], v[78:81], v[166:169], v[58:61]
	v_mfma_f32_16x16x32_bf16 v[46:49], v[70:73], v[192:195], v[46:49]
	v_mfma_f32_16x16x32_bf16 v[42:45], v[78:81], v[192:195], v[42:45]
	v_mfma_f32_16x16x32_bf16 v[30:33], v[70:73], v[200:203], v[30:33]
	v_mfma_f32_16x16x32_bf16 v[26:29], v[78:81], v[200:203], v[26:29]
	v_mfma_f32_16x16x32_bf16 v[14:17], v[70:73], v[208:211], v[14:17]
	v_mfma_f32_16x16x32_bf16 v[10:13], v[78:81], v[208:211], v[10:13]
	v_mfma_f32_16x16x32_bf16 v[54:57], v[130:133], v[162:165], v[54:57]
	v_mfma_f32_16x16x32_bf16 v[50:53], v[146:149], v[162:165], v[50:53]
	v_mfma_f32_16x16x32_bf16 v[38:41], v[130:133], v[170:173], v[38:41]
	v_mfma_f32_16x16x32_bf16 v[34:37], v[146:149], v[170:173], v[34:37]
	v_mfma_f32_16x16x32_bf16 v[22:25], v[130:133], v[196:199], v[22:25]
	v_mfma_f32_16x16x32_bf16 v[18:21], v[146:149], v[196:199], v[18:21]
	v_mfma_f32_16x16x32_bf16 v[6:9], v[130:133], v[204:207], v[6:9]
	v_mfma_f32_16x16x32_bf16 v[2:5], v[146:149], v[204:207], v[2:5]
	v_mfma_f32_16x16x32_bf16 v[54:57], v[142:145], v[166:169], v[54:57]
	v_mfma_f32_16x16x32_bf16 v[50:53], v[158:161], v[166:169], v[50:53]
	v_mfma_f32_16x16x32_bf16 v[38:41], v[142:145], v[192:195], v[38:41]
	v_mfma_f32_16x16x32_bf16 v[34:37], v[158:161], v[192:195], v[34:37]
	v_mfma_f32_16x16x32_bf16 v[22:25], v[142:145], v[200:203], v[22:25]
	v_mfma_f32_16x16x32_bf16 v[18:21], v[158:161], v[200:203], v[18:21]
	v_mfma_f32_16x16x32_bf16 v[6:9], v[142:145], v[208:211], v[6:9]
	v_mfma_f32_16x16x32_bf16 v[2:5], v[158:161], v[208:211], v[2:5]
	s_setprio 0
	s_barrier
	s_add_i32 s63, s63, 2
	s_add_u32 s61, s61, 0x100
	s_addc_u32 s62, s62, 0
	s_add_u32 s8, s8, 0x100
	s_addc_u32 s9, s9, 0
	s_cmp_gt_u32 s63, 29
	s_cbranch_scc0 .LBB0_617
	s_and_b64 vcc, exec, s[14:15]
	s_cbranch_vccz .LBB0_620
	s_barrier

.LBB0_744:
	s_add_u32 s44, s38, 0x100
	s_addc_u32 s45, s39, 0
	s_and_b64 s[46:47], s[46:47], exec
	s_cselect_b32 s51, s31, s45
	s_cselect_b32 s50, s88, s44
	s_cselect_b32 s47, s29, s43
	s_cselect_b32 s46, s90, s41
	s_add_i32 s93, 0, 0x10000
	s_add_i32 s94, 0, 0x14000
	v_add_u32_e32 v84, s93, v226
	v_add_u32_e32 v88, s94, v226
	ds_read_b128 v[72:75], v84
	ds_read_b128 v[76:79], v84 offset:1024
	ds_read_b128 v[80:83], v84 offset:2048
	ds_read_b128 v[84:87], v84 offset:3072
	ds_read_b128 v[154:157], v88
	ds_read_b128 v[158:161], v88 offset:1024
	ds_read_b128 v[182:185], v88 offset:2048
	ds_read_b128 v[186:189], v88 offset:3072
	v_lshl_add_u64 v[88:89], s[38:39], 0, v[180:181]
	s_add_i32 m0, s56, 0xc000
	ds_read_b128 v[190:193], v230
	ds_read_b128 v[194:197], v230 offset:1024
	ds_read_b128 v[198:201], v230 offset:2048
	ds_read_b128 v[202:205], v230 offset:3072
	ds_read_b128 v[206:209], v230 offset:4096
	ds_read_b128 v[210:213], v230 offset:5120
	ds_read_b128 v[214:217], v230 offset:6144
	ds_read_b128 v[236:239], v230 offset:7168
	global_load_lds_dwordx4 v[88:89], off
	v_lshl_add_u64 v[88:89], s[38:39], 0, v[178:179]
	s_add_i32 m0, s56, 0xe000
	s_nop 0
	global_load_lds_dwordx4 v[88:89], off
	s_waitcnt vmcnt(8) lgkmcnt(0)
	s_barrier
	s_setprio 1
	v_mfma_f32_16x16x32_bf16 v[150:153], v[72:75], v[190:193], v[150:153]
	v_mfma_f32_16x16x32_bf16 v[146:149], v[80:83], v[190:193], v[146:149]
	v_mfma_f32_16x16x32_bf16 v[118:121], v[72:75], v[198:201], v[118:121]
	v_mfma_f32_16x16x32_bf16 v[114:117], v[80:83], v[198:201], v[114:117]
	v_mfma_f32_16x16x32_bf16 v[142:145], v[72:75], v[206:209], v[142:145]
	v_mfma_f32_16x16x32_bf16 v[134:137], v[80:83], v[206:209], v[134:137]
	v_mfma_f32_16x16x32_bf16 v[126:129], v[72:75], v[214:217], v[126:129]
	v_mfma_f32_16x16x32_bf16 v[122:125], v[80:83], v[214:217], v[122:125]
	v_mfma_f32_16x16x32_bf16 v[150:153], v[76:79], v[194:197], v[150:153]
	v_mfma_f32_16x16x32_bf16 v[146:149], v[84:87], v[194:197], v[146:149]
	v_mfma_f32_16x16x32_bf16 v[118:121], v[76:79], v[202:205], v[118:121]
	v_mfma_f32_16x16x32_bf16 v[114:117], v[84:87], v[202:205], v[114:117]
	v_mfma_f32_16x16x32_bf16 v[142:145], v[76:79], v[210:213], v[142:145]
	v_mfma_f32_16x16x32_bf16 v[134:137], v[84:87], v[210:213], v[134:137]
	v_mfma_f32_16x16x32_bf16 v[126:129], v[76:79], v[236:239], v[126:129]
	v_mfma_f32_16x16x32_bf16 v[122:125], v[84:87], v[236:239], v[122:125]
	v_mfma_f32_16x16x32_bf16 v[138:141], v[154:157], v[190:193], v[138:141]
	v_mfma_f32_16x16x32_bf16 v[130:133], v[182:185], v[190:193], v[130:133]
	v_mfma_f32_16x16x32_bf16 v[110:113], v[154:157], v[198:201], v[110:113]
	v_mfma_f32_16x16x32_bf16 v[106:109], v[182:185], v[198:201], v[106:109]
	v_mfma_f32_16x16x32_bf16 v[102:105], v[154:157], v[206:209], v[102:105]
	v_mfma_f32_16x16x32_bf16 v[98:101], v[182:185], v[206:209], v[98:101]
	v_mfma_f32_16x16x32_bf16 v[94:97], v[154:157], v[214:217], v[94:97]
	v_mfma_f32_16x16x32_bf16 v[88:91], v[182:185], v[214:217], v[90:93]
	v_mfma_f32_16x16x32_bf16 v[138:141], v[158:161], v[194:197], v[138:141]
	v_mfma_f32_16x16x32_bf16 v[130:133], v[186:189], v[194:197], v[130:133]
	v_mfma_f32_16x16x32_bf16 v[110:113], v[158:161], v[202:205], v[110:113]
	v_mfma_f32_16x16x32_bf16 v[106:109], v[186:189], v[202:205], v[106:109]
	v_mfma_f32_16x16x32_bf16 v[102:105], v[158:161], v[210:213], v[102:105]
	v_mfma_f32_16x16x32_bf16 v[98:101], v[186:189], v[210:213], v[98:101]
	v_mfma_f32_16x16x32_bf16 v[94:97], v[158:161], v[236:239], v[94:97]
	v_mfma_f32_16x16x32_bf16 v[88:91], v[186:189], v[236:239], v[88:91]
	s_setprio 0
	s_barrier
	s_add_i32 s38, s93, s55
	v_lshl_add_u64 v[220:221], s[46:47], 0, v[166:167]
	s_mov_b32 m0, s38
	ds_read_b128 v[190:193], v230 offset:16384
	ds_read_b128 v[194:197], v230 offset:17408
	ds_read_b128 v[198:201], v230 offset:18432
	ds_read_b128 v[202:205], v230 offset:19456
	ds_read_b128 v[206:209], v230 offset:20480
	ds_read_b128 v[210:213], v230 offset:21504
	ds_read_b128 v[214:217], v230 offset:22528
	ds_read_b128 v[236:239], v230 offset:23552
	global_load_lds_dwordx4 v[220:221], off
	s_add_i32 m0, s38, 0x2000
	s_add_u32 s38, s46, 0x80000
	v_lshl_add_u64 v[240:241], s[46:47], 0, v[162:163]
	s_addc_u32 s39, s47, 0
	s_add_i32 s93, s94, s55
	global_load_lds_dwordx4 v[240:241], off
	v_lshl_add_u64 v[92:93], s[38:39], 0, v[166:167]
	s_mov_b32 m0, s93
	v_lshl_add_u64 v[242:243], s[50:51], 0, v[168:169]
	global_load_lds_dwordx4 v[92:93], off
	v_lshl_add_u64 v[92:93], s[38:39], 0, v[162:163]
	s_add_i32 m0, s93, 0x2000
	v_lshl_add_u64 v[244:245], s[50:51], 0, v[164:165]
	global_load_lds_dwordx4 v[92:93], off
	s_mov_b32 m0, s56
	s_nop 0
	global_load_lds_dwordx4 v[242:243], off
	s_mov_b32 m0, s57
	s_nop 0
	global_load_lds_dwordx4 v[244:245], off
	s_waitcnt vmcnt(8) lgkmcnt(0)
	s_barrier
	s_setprio 1
	v_mfma_f32_16x16x32_bf16 v[62:65], v[72:75], v[190:193], v[62:65]
	v_mfma_f32_16x16x32_bf16 v[58:61], v[80:83], v[190:193], v[58:61]
	v_mfma_f32_16x16x32_bf16 v[54:57], v[72:75], v[198:201], v[54:57]
	v_mfma_f32_16x16x32_bf16 v[46:49], v[80:83], v[198:201], v[46:49]
	v_mfma_f32_16x16x32_bf16 v[38:41], v[72:75], v[206:209], v[38:41]
	v_mfma_f32_16x16x32_bf16 v[30:33], v[80:83], v[206:209], v[30:33]
	v_mfma_f32_16x16x32_bf16 v[22:25], v[72:75], v[214:217], v[22:25]
	v_mfma_f32_16x16x32_bf16 v[14:17], v[80:83], v[214:217], v[14:17]
	v_mfma_f32_16x16x32_bf16 v[62:65], v[76:79], v[194:197], v[62:65]
	v_mfma_f32_16x16x32_bf16 v[58:61], v[84:87], v[194:197], v[58:61]
	v_mfma_f32_16x16x32_bf16 v[54:57], v[76:79], v[202:205], v[54:57]
	v_mfma_f32_16x16x32_bf16 v[46:49], v[84:87], v[202:205], v[46:49]
	v_mfma_f32_16x16x32_bf16 v[38:41], v[76:79], v[210:213], v[38:41]
	v_mfma_f32_16x16x32_bf16 v[30:33], v[84:87], v[210:213], v[30:33]
	v_mfma_f32_16x16x32_bf16 v[22:25], v[76:79], v[236:239], v[22:25]
	v_mfma_f32_16x16x32_bf16 v[14:17], v[84:87], v[236:239], v[14:17]
	v_mfma_f32_16x16x32_bf16 v[50:53], v[154:157], v[190:193], v[50:53]
	v_mfma_f32_16x16x32_bf16 v[42:45], v[182:185], v[190:193], v[42:45]
	v_mfma_f32_16x16x32_bf16 v[34:37], v[154:157], v[198:201], v[34:37]
	v_mfma_f32_16x16x32_bf16 v[26:29], v[182:185], v[198:201], v[26:29]
	v_mfma_f32_16x16x32_bf16 v[18:21], v[154:157], v[206:209], v[18:21]
	v_mfma_f32_16x16x32_bf16 v[10:13], v[182:185], v[206:209], v[10:13]
	v_mfma_f32_16x16x32_bf16 v[6:9], v[154:157], v[214:217], v[6:9]
	v_mfma_f32_16x16x32_bf16 v[2:5], v[182:185], v[214:217], v[2:5]
	v_mfma_f32_16x16x32_bf16 v[50:53], v[158:161], v[194:197], v[50:53]
	v_mfma_f32_16x16x32_bf16 v[42:45], v[186:189], v[194:197], v[42:45]
	v_mfma_f32_16x16x32_bf16 v[34:37], v[158:161], v[202:205], v[34:37]
	v_mfma_f32_16x16x32_bf16 v[26:29], v[186:189], v[202:205], v[26:29]
	v_mfma_f32_16x16x32_bf16 v[18:21], v[158:161], v[210:213], v[18:21]
	v_mfma_f32_16x16x32_bf16 v[10:13], v[186:189], v[210:213], v[10:13]
	v_mfma_f32_16x16x32_bf16 v[6:9], v[158:161], v[236:239], v[6:9]
	v_mfma_f32_16x16x32_bf16 v[2:5], v[186:189], v[236:239], v[2:5]
	s_setprio 0
	s_barrier
	s_add_i32 s93, 0, 0x18000
	s_add_i32 s94, 0, 0x1c000
	v_add_u32_e32 v84, s93, v226
	v_add_u32_e32 v92, s94, v226
	ds_read_b128 v[72:75], v84
	ds_read_b128 v[76:79], v84 offset:1024
	ds_read_b128 v[80:83], v84 offset:2048
	ds_read_b128 v[84:87], v84 offset:3072
	ds_read_b128 v[154:157], v92
	ds_read_b128 v[158:161], v92 offset:1024
	ds_read_b128 v[182:185], v92 offset:2048
	ds_read_b128 v[186:189], v92 offset:3072
	s_add_u32 s38, s50, 0x80000
	s_addc_u32 s39, s51, 0
	s_mov_b32 m0, s60
	v_lshl_add_u64 v[92:93], s[38:39], 0, v[168:169]
	ds_read_b128 v[190:193], v230 offset:32768
	ds_read_b128 v[194:197], v230 offset:33792
	ds_read_b128 v[198:201], v230 offset:34816
	ds_read_b128 v[202:205], v230 offset:35840
	ds_read_b128 v[206:209], v230 offset:36864
	ds_read_b128 v[210:213], v230 offset:37888
	ds_read_b128 v[214:217], v230 offset:38912
	ds_read_b128 v[236:239], v230 offset:39936
	global_load_lds_dwordx4 v[92:93], off
	v_lshl_add_u64 v[92:93], s[38:39], 0, v[164:165]
	s_mov_b32 m0, s61
	s_nop 0
	global_load_lds_dwordx4 v[92:93], off
	s_waitcnt vmcnt(8) lgkmcnt(0)
	s_barrier
	s_setprio 1
	v_mfma_f32_16x16x32_bf16 v[150:153], v[72:75], v[190:193], v[150:153]
	v_mfma_f32_16x16x32_bf16 v[146:149], v[80:83], v[190:193], v[146:149]
	v_mfma_f32_16x16x32_bf16 v[118:121], v[72:75], v[198:201], v[118:121]
	v_mfma_f32_16x16x32_bf16 v[114:117], v[80:83], v[198:201], v[114:117]
	v_mfma_f32_16x16x32_bf16 v[142:145], v[72:75], v[206:209], v[142:145]
	v_mfma_f32_16x16x32_bf16 v[134:137], v[80:83], v[206:209], v[134:137]
	v_mfma_f32_16x16x32_bf16 v[126:129], v[72:75], v[214:217], v[126:129]
	v_mfma_f32_16x16x32_bf16 v[122:125], v[80:83], v[214:217], v[122:125]
	v_mfma_f32_16x16x32_bf16 v[150:153], v[76:79], v[194:197], v[150:153]
	v_mfma_f32_16x16x32_bf16 v[146:149], v[84:87], v[194:197], v[146:149]
	v_mfma_f32_16x16x32_bf16 v[118:121], v[76:79], v[202:205], v[118:121]
	v_mfma_f32_16x16x32_bf16 v[114:117], v[84:87], v[202:205], v[114:117]
	v_mfma_f32_16x16x32_bf16 v[142:145], v[76:79], v[210:213], v[142:145]
	v_mfma_f32_16x16x32_bf16 v[134:137], v[84:87], v[210:213], v[134:137]
	v_mfma_f32_16x16x32_bf16 v[126:129], v[76:79], v[236:239], v[126:129]
	v_mfma_f32_16x16x32_bf16 v[122:125], v[84:87], v[236:239], v[122:125]
	v_mfma_f32_16x16x32_bf16 v[138:141], v[154:157], v[190:193], v[138:141]
	v_mfma_f32_16x16x32_bf16 v[130:133], v[182:185], v[190:193], v[130:133]
	v_mfma_f32_16x16x32_bf16 v[110:113], v[154:157], v[198:201], v[110:113]
	v_mfma_f32_16x16x32_bf16 v[106:109], v[182:185], v[198:201], v[106:109]
	v_mfma_f32_16x16x32_bf16 v[102:105], v[154:157], v[206:209], v[102:105]
	v_mfma_f32_16x16x32_bf16 v[98:101], v[182:185], v[206:209], v[98:101]
	v_mfma_f32_16x16x32_bf16 v[92:95], v[154:157], v[214:217], v[94:97]
	v_mfma_f32_16x16x32_bf16 v[88:91], v[182:185], v[214:217], v[88:91]
	v_mfma_f32_16x16x32_bf16 v[138:141], v[158:161], v[194:197], v[138:141]
	v_mfma_f32_16x16x32_bf16 v[130:133], v[186:189], v[194:197], v[130:133]
	v_mfma_f32_16x16x32_bf16 v[110:113], v[158:161], v[202:205], v[110:113]
	v_mfma_f32_16x16x32_bf16 v[106:109], v[186:189], v[202:205], v[106:109]
	v_mfma_f32_16x16x32_bf16 v[102:105], v[158:161], v[210:213], v[102:105]
	v_mfma_f32_16x16x32_bf16 v[98:101], v[186:189], v[210:213], v[98:101]
	v_mfma_f32_16x16x32_bf16 v[94:97], v[158:161], v[236:239], v[92:95]
	v_mfma_f32_16x16x32_bf16 v[90:93], v[186:189], v[236:239], v[88:91]
	s_setprio 0
	s_barrier
	s_add_i32 s38, s93, s55
	v_lshl_add_u64 v[88:89], v[220:221], 0, s[96:97]
	s_mov_b32 m0, s38
	ds_read_b128 v[190:193], v230 offset:49152
	ds_read_b128 v[194:197], v230 offset:50176
	ds_read_b128 v[198:201], v230 offset:51200
	ds_read_b128 v[202:205], v230 offset:52224
	ds_read_b128 v[206:209], v230 offset:53248
	ds_read_b128 v[210:213], v230 offset:54272
	ds_read_b128 v[214:217], v230 offset:55296
	ds_read_b128 v[236:239], v230 offset:56320
	global_load_lds_dwordx4 v[88:89], off
	s_add_i32 m0, s38, 0x2000
	s_add_u32 s38, s46, 0x80080
	v_lshl_add_u64 v[88:89], v[240:241], 0, s[96:97]
	s_addc_u32 s39, s47, 0
	s_add_i32 s46, s94, s55
	global_load_lds_dwordx4 v[88:89], off
	v_lshl_add_u64 v[88:89], s[38:39], 0, v[166:167]
	s_mov_b32 m0, s46
	s_nop 0
	global_load_lds_dwordx4 v[88:89], off
	v_lshl_add_u64 v[88:89], s[38:39], 0, v[162:163]
	s_add_i32 m0, s46, 0x2000
	s_nop 0
	global_load_lds_dwordx4 v[88:89], off
	v_lshl_add_u64 v[88:89], v[242:243], 0, s[96:97]
	s_mov_b32 m0, s75
	s_nop 0
	global_load_lds_dwordx4 v[88:89], off
	v_lshl_add_u64 v[88:89], v[244:245], 0, s[96:97]
	s_mov_b32 m0, s76
	s_nop 0
	global_load_lds_dwordx4 v[88:89], off
	s_waitcnt vmcnt(8) lgkmcnt(0)
	s_barrier
	s_setprio 1
	v_mfma_f32_16x16x32_bf16 v[62:65], v[72:75], v[190:193], v[62:65]
	v_mfma_f32_16x16x32_bf16 v[58:61], v[80:83], v[190:193], v[58:61]
	v_mfma_f32_16x16x32_bf16 v[54:57], v[72:75], v[198:201], v[54:57]
	v_mfma_f32_16x16x32_bf16 v[46:49], v[80:83], v[198:201], v[46:49]
	v_mfma_f32_16x16x32_bf16 v[38:41], v[72:75], v[206:209], v[38:41]
	v_mfma_f32_16x16x32_bf16 v[30:33], v[80:83], v[206:209], v[30:33]
	v_mfma_f32_16x16x32_bf16 v[22:25], v[72:75], v[214:217], v[22:25]
	v_mfma_f32_16x16x32_bf16 v[14:17], v[80:83], v[214:217], v[14:17]
	v_mfma_f32_16x16x32_bf16 v[62:65], v[76:79], v[194:197], v[62:65]
	v_mfma_f32_16x16x32_bf16 v[58:61], v[84:87], v[194:197], v[58:61]
	v_mfma_f32_16x16x32_bf16 v[54:57], v[76:79], v[202:205], v[54:57]
	v_mfma_f32_16x16x32_bf16 v[46:49], v[84:87], v[202:205], v[46:49]
	v_mfma_f32_16x16x32_bf16 v[38:41], v[76:79], v[210:213], v[38:41]
	v_mfma_f32_16x16x32_bf16 v[30:33], v[84:87], v[210:213], v[30:33]
	v_mfma_f32_16x16x32_bf16 v[22:25], v[76:79], v[236:239], v[22:25]
	v_mfma_f32_16x16x32_bf16 v[14:17], v[84:87], v[236:239], v[14:17]
	v_mfma_f32_16x16x32_bf16 v[50:53], v[154:157], v[190:193], v[50:53]
	v_mfma_f32_16x16x32_bf16 v[42:45], v[182:185], v[190:193], v[42:45]
	v_mfma_f32_16x16x32_bf16 v[34:37], v[154:157], v[198:201], v[34:37]
	v_mfma_f32_16x16x32_bf16 v[26:29], v[182:185], v[198:201], v[26:29]
	v_mfma_f32_16x16x32_bf16 v[18:21], v[154:157], v[206:209], v[18:21]
	v_mfma_f32_16x16x32_bf16 v[10:13], v[182:185], v[206:209], v[10:13]
	v_mfma_f32_16x16x32_bf16 v[6:9], v[154:157], v[214:217], v[6:9]
	v_mfma_f32_16x16x32_bf16 v[2:5], v[182:185], v[214:217], v[2:5]
	v_mfma_f32_16x16x32_bf16 v[50:53], v[158:161], v[194:197], v[50:53]
	v_mfma_f32_16x16x32_bf16 v[42:45], v[186:189], v[194:197], v[42:45]
	v_mfma_f32_16x16x32_bf16 v[34:37], v[158:161], v[202:205], v[34:37]
	v_mfma_f32_16x16x32_bf16 v[26:29], v[186:189], v[202:205], v[26:29]
	v_mfma_f32_16x16x32_bf16 v[18:21], v[158:161], v[210:213], v[18:21]
	v_mfma_f32_16x16x32_bf16 v[10:13], v[186:189], v[210:213], v[10:13]
	v_mfma_f32_16x16x32_bf16 v[6:9], v[158:161], v[236:239], v[6:9]
	v_mfma_f32_16x16x32_bf16 v[2:5], v[186:189], v[236:239], v[2:5]
	s_setprio 0
	s_barrier
	s_add_i32 s91, s91, 2
	s_add_u32 s41, s41, 0x100
	s_addc_u32 s43, s43, 0
	s_cmp_gt_u32 s91, 29
	s_mov_b64 s[38:39], s[44:45]
	s_cbranch_scc1 .LBB0_755

.LBB0_905:
	s_add_u32 s8, s26, 0x100
	s_addc_u32 s9, s27, 0
	s_add_i32 s61, 0, 0x10000
	s_cmpk_eq_i32 s60, 0x54
	s_cselect_b32 s31, s23, s9
	s_cselect_b32 s30, s22, s8
	v_add_u32_e32 v0, s61, v212
	s_cselect_b32 s29, s25, s21
	s_cselect_b32 s28, s24, s19
	s_add_i32 s62, 0, 0x14000
	ds_read_b128 v[66:69], v0
	ds_read_b128 v[70:73], v0 offset:1024
	ds_read_b128 v[74:77], v0 offset:2048
	ds_read_b128 v[78:81], v0 offset:3072
	v_add_u32_e32 v0, s62, v212
	ds_read_b128 v[130:133], v0
	ds_read_b128 v[142:145], v0 offset:1024
	ds_read_b128 v[146:149], v0 offset:2048
	ds_read_b128 v[158:161], v0 offset:3072
	v_lshl_add_u64 v[220:221], s[26:27], 0, v[190:191]
	s_add_i32 m0, s39, 0xc000
	ds_read_b128 v[162:165], v215
	ds_read_b128 v[166:169], v215 offset:1024
	ds_read_b128 v[170:173], v215 offset:2048
	ds_read_b128 v[192:195], v215 offset:3072
	ds_read_b128 v[196:199], v215 offset:4096
	ds_read_b128 v[200:203], v215 offset:5120
	ds_read_b128 v[204:207], v215 offset:6144
	ds_read_b128 v[208:211], v215 offset:7168
	global_load_lds_dwordx4 v[220:221], off
	v_lshl_add_u64 v[220:221], s[26:27], 0, v[188:189]
	s_add_i32 m0, s39, 0xe000
	s_nop 0
	global_load_lds_dwordx4 v[220:221], off
	s_waitcnt vmcnt(8) lgkmcnt(0)
	s_barrier
	s_setprio 1
	v_mfma_f32_16x16x32_bf16 v[154:157], v[66:69], v[162:165], v[154:157]
	v_mfma_f32_16x16x32_bf16 v[150:153], v[74:77], v[162:165], v[150:153]
	v_mfma_f32_16x16x32_bf16 v[138:141], v[66:69], v[170:173], v[138:141]
	v_mfma_f32_16x16x32_bf16 v[134:137], v[74:77], v[170:173], v[134:137]
	v_mfma_f32_16x16x32_bf16 v[110:113], v[66:69], v[196:199], v[110:113]
	v_mfma_f32_16x16x32_bf16 v[106:109], v[74:77], v[196:199], v[106:109]
	v_mfma_f32_16x16x32_bf16 v[94:97], v[66:69], v[204:207], v[94:97]
	v_mfma_f32_16x16x32_bf16 v[90:93], v[74:77], v[204:207], v[90:93]
	v_mfma_f32_16x16x32_bf16 v[154:157], v[70:73], v[166:169], v[154:157]
	v_mfma_f32_16x16x32_bf16 v[150:153], v[78:81], v[166:169], v[150:153]
	v_mfma_f32_16x16x32_bf16 v[138:141], v[70:73], v[192:195], v[138:141]
	v_mfma_f32_16x16x32_bf16 v[134:137], v[78:81], v[192:195], v[134:137]
	v_mfma_f32_16x16x32_bf16 v[110:113], v[70:73], v[200:203], v[110:113]
	v_mfma_f32_16x16x32_bf16 v[106:109], v[78:81], v[200:203], v[106:109]
	v_mfma_f32_16x16x32_bf16 v[94:97], v[70:73], v[208:211], v[94:97]
	v_mfma_f32_16x16x32_bf16 v[90:93], v[78:81], v[208:211], v[90:93]
	v_mfma_f32_16x16x32_bf16 v[126:129], v[130:133], v[162:165], v[126:129]
	v_mfma_f32_16x16x32_bf16 v[114:117], v[146:149], v[162:165], v[114:117]
	v_mfma_f32_16x16x32_bf16 v[122:125], v[130:133], v[170:173], v[122:125]
	v_mfma_f32_16x16x32_bf16 v[118:121], v[146:149], v[170:173], v[118:121]
	v_mfma_f32_16x16x32_bf16 v[102:105], v[130:133], v[196:199], v[102:105]
	v_mfma_f32_16x16x32_bf16 v[98:101], v[146:149], v[196:199], v[98:101]
	v_mfma_f32_16x16x32_bf16 v[86:89], v[130:133], v[204:207], v[86:89]
	v_mfma_f32_16x16x32_bf16 v[82:85], v[146:149], v[204:207], v[82:85]
	v_mfma_f32_16x16x32_bf16 v[126:129], v[142:145], v[166:169], v[126:129]
	v_mfma_f32_16x16x32_bf16 v[114:117], v[158:161], v[166:169], v[114:117]
	v_mfma_f32_16x16x32_bf16 v[122:125], v[142:145], v[192:195], v[122:125]
	v_mfma_f32_16x16x32_bf16 v[118:121], v[158:161], v[192:195], v[118:121]
	v_mfma_f32_16x16x32_bf16 v[102:105], v[142:145], v[200:203], v[102:105]
	v_mfma_f32_16x16x32_bf16 v[98:101], v[158:161], v[200:203], v[98:101]
	v_mfma_f32_16x16x32_bf16 v[86:89], v[142:145], v[208:211], v[86:89]
	v_mfma_f32_16x16x32_bf16 v[82:85], v[158:161], v[208:211], v[82:85]
	s_setprio 0
	s_barrier
	s_add_i32 s26, s61, s38
	v_lshl_add_u64 v[220:221], s[28:29], 0, v[182:183]
	s_mov_b32 m0, s26
	ds_read_b128 v[162:165], v215 offset:16384
	ds_read_b128 v[166:169], v215 offset:17408
	ds_read_b128 v[170:173], v215 offset:18432
	ds_read_b128 v[192:195], v215 offset:19456
	ds_read_b128 v[196:199], v215 offset:20480
	ds_read_b128 v[200:203], v215 offset:21504
	ds_read_b128 v[204:207], v215 offset:22528
	ds_read_b128 v[208:211], v215 offset:23552
	global_load_lds_dwordx4 v[220:221], off
	s_add_i32 m0, s26, 0x2000
	s_add_u32 s26, s28, 0x160000
	v_lshl_add_u64 v[230:231], s[28:29], 0, v[178:179]
	s_addc_u32 s27, s29, 0
	s_add_i32 s61, s62, s38
	global_load_lds_dwordx4 v[230:231], off
	v_lshl_add_u64 v[232:233], s[26:27], 0, v[182:183]
	s_mov_b32 m0, s61
	v_lshl_add_u64 v[234:235], s[30:31], 0, v[180:181]
	global_load_lds_dwordx4 v[232:233], off
	v_lshl_add_u64 v[232:233], s[26:27], 0, v[178:179]
	s_add_i32 m0, s61, 0x2000
	s_nop 0
	global_load_lds_dwordx4 v[232:233], off
	v_lshl_add_u64 v[232:233], s[30:31], 0, v[184:185]
	s_mov_b32 m0, s39
	s_nop 0
	global_load_lds_dwordx4 v[232:233], off
	s_mov_b32 m0, s40
	s_nop 0
	global_load_lds_dwordx4 v[234:235], off
	s_waitcnt vmcnt(8) lgkmcnt(0)
	s_barrier
	s_setprio 1
	v_mfma_f32_16x16x32_bf16 v[62:65], v[66:69], v[162:165], v[62:65]
	v_mfma_f32_16x16x32_bf16 v[58:61], v[74:77], v[162:165], v[58:61]
	v_mfma_f32_16x16x32_bf16 v[46:49], v[66:69], v[170:173], v[46:49]
	v_mfma_f32_16x16x32_bf16 v[42:45], v[74:77], v[170:173], v[42:45]
	v_mfma_f32_16x16x32_bf16 v[30:33], v[66:69], v[196:199], v[30:33]
	v_mfma_f32_16x16x32_bf16 v[26:29], v[74:77], v[196:199], v[26:29]
	v_mfma_f32_16x16x32_bf16 v[14:17], v[66:69], v[204:207], v[14:17]
	v_mfma_f32_16x16x32_bf16 v[10:13], v[74:77], v[204:207], v[10:13]
	v_mfma_f32_16x16x32_bf16 v[62:65], v[70:73], v[166:169], v[62:65]
	v_mfma_f32_16x16x32_bf16 v[58:61], v[78:81], v[166:169], v[58:61]
	v_mfma_f32_16x16x32_bf16 v[46:49], v[70:73], v[192:195], v[46:49]
	v_mfma_f32_16x16x32_bf16 v[42:45], v[78:81], v[192:195], v[42:45]
	v_mfma_f32_16x16x32_bf16 v[30:33], v[70:73], v[200:203], v[30:33]
	v_mfma_f32_16x16x32_bf16 v[26:29], v[78:81], v[200:203], v[26:29]
	v_mfma_f32_16x16x32_bf16 v[14:17], v[70:73], v[208:211], v[14:17]
	v_mfma_f32_16x16x32_bf16 v[10:13], v[78:81], v[208:211], v[10:13]
	v_mfma_f32_16x16x32_bf16 v[54:57], v[130:133], v[162:165], v[54:57]
	v_mfma_f32_16x16x32_bf16 v[50:53], v[146:149], v[162:165], v[50:53]
	v_mfma_f32_16x16x32_bf16 v[38:41], v[130:133], v[170:173], v[38:41]
	v_mfma_f32_16x16x32_bf16 v[34:37], v[146:149], v[170:173], v[34:37]
	v_mfma_f32_16x16x32_bf16 v[22:25], v[130:133], v[196:199], v[22:25]
	v_mfma_f32_16x16x32_bf16 v[18:21], v[146:149], v[196:199], v[18:21]
	v_mfma_f32_16x16x32_bf16 v[6:9], v[130:133], v[204:207], v[6:9]
	v_mfma_f32_16x16x32_bf16 v[2:5], v[146:149], v[204:207], v[2:5]
	v_mfma_f32_16x16x32_bf16 v[54:57], v[142:145], v[166:169], v[54:57]
	v_mfma_f32_16x16x32_bf16 v[50:53], v[158:161], v[166:169], v[50:53]
	v_mfma_f32_16x16x32_bf16 v[38:41], v[142:145], v[192:195], v[38:41]
	v_mfma_f32_16x16x32_bf16 v[34:37], v[158:161], v[192:195], v[34:37]
	v_mfma_f32_16x16x32_bf16 v[22:25], v[142:145], v[200:203], v[22:25]
	v_mfma_f32_16x16x32_bf16 v[18:21], v[158:161], v[200:203], v[18:21]
	v_mfma_f32_16x16x32_bf16 v[6:9], v[142:145], v[208:211], v[6:9]
	v_mfma_f32_16x16x32_bf16 v[2:5], v[158:161], v[208:211], v[2:5]
	s_setprio 0
	s_barrier
	s_add_i32 s61, 0, 0x18000
	v_add_u32_e32 v0, s61, v212
	s_add_i32 s62, 0, 0x1c000
	ds_read_b128 v[66:69], v0
	ds_read_b128 v[70:73], v0 offset:1024
	ds_read_b128 v[74:77], v0 offset:2048
	ds_read_b128 v[78:81], v0 offset:3072
	v_add_u32_e32 v0, s62, v212
	ds_read_b128 v[130:133], v0
	ds_read_b128 v[142:145], v0 offset:1024
	ds_read_b128 v[146:149], v0 offset:2048
	ds_read_b128 v[158:161], v0 offset:3072
	s_add_u32 s26, s30, 0x160000
	s_addc_u32 s27, s31, 0
	s_mov_b32 m0, s41
	v_lshl_add_u64 v[236:237], s[26:27], 0, v[184:185]
	ds_read_b128 v[162:165], v215 offset:32768
	ds_read_b128 v[166:169], v215 offset:33792
	ds_read_b128 v[170:173], v215 offset:34816
	ds_read_b128 v[192:195], v215 offset:35840
	ds_read_b128 v[196:199], v215 offset:36864
	ds_read_b128 v[200:203], v215 offset:37888
	ds_read_b128 v[204:207], v215 offset:38912
	ds_read_b128 v[208:211], v215 offset:39936
	global_load_lds_dwordx4 v[236:237], off
	v_lshl_add_u64 v[236:237], s[26:27], 0, v[180:181]
	s_mov_b32 m0, s42
	s_nop 0
	global_load_lds_dwordx4 v[236:237], off
	s_waitcnt vmcnt(8) lgkmcnt(0)
	s_barrier
	s_setprio 1
	v_mfma_f32_16x16x32_bf16 v[154:157], v[66:69], v[162:165], v[154:157]
	v_mfma_f32_16x16x32_bf16 v[150:153], v[74:77], v[162:165], v[150:153]
	v_mfma_f32_16x16x32_bf16 v[138:141], v[66:69], v[170:173], v[138:141]
	v_mfma_f32_16x16x32_bf16 v[134:137], v[74:77], v[170:173], v[134:137]
	v_mfma_f32_16x16x32_bf16 v[110:113], v[66:69], v[196:199], v[110:113]
	v_mfma_f32_16x16x32_bf16 v[106:109], v[74:77], v[196:199], v[106:109]
	v_mfma_f32_16x16x32_bf16 v[94:97], v[66:69], v[204:207], v[94:97]
	v_mfma_f32_16x16x32_bf16 v[90:93], v[74:77], v[204:207], v[90:93]
	v_mfma_f32_16x16x32_bf16 v[154:157], v[70:73], v[166:169], v[154:157]
	v_mfma_f32_16x16x32_bf16 v[150:153], v[78:81], v[166:169], v[150:153]
	v_mfma_f32_16x16x32_bf16 v[138:141], v[70:73], v[192:195], v[138:141]
	v_mfma_f32_16x16x32_bf16 v[134:137], v[78:81], v[192:195], v[134:137]
	v_mfma_f32_16x16x32_bf16 v[110:113], v[70:73], v[200:203], v[110:113]
	v_mfma_f32_16x16x32_bf16 v[106:109], v[78:81], v[200:203], v[106:109]
	v_mfma_f32_16x16x32_bf16 v[94:97], v[70:73], v[208:211], v[94:97]
	v_mfma_f32_16x16x32_bf16 v[90:93], v[78:81], v[208:211], v[90:93]
	v_mfma_f32_16x16x32_bf16 v[126:129], v[130:133], v[162:165], v[126:129]
	v_mfma_f32_16x16x32_bf16 v[114:117], v[146:149], v[162:165], v[114:117]
	v_mfma_f32_16x16x32_bf16 v[122:125], v[130:133], v[170:173], v[122:125]
	v_mfma_f32_16x16x32_bf16 v[118:121], v[146:149], v[170:173], v[118:121]
	v_mfma_f32_16x16x32_bf16 v[102:105], v[130:133], v[196:199], v[102:105]
	v_mfma_f32_16x16x32_bf16 v[98:101], v[146:149], v[196:199], v[98:101]
	v_mfma_f32_16x16x32_bf16 v[86:89], v[130:133], v[204:207], v[86:89]
	v_mfma_f32_16x16x32_bf16 v[82:85], v[146:149], v[204:207], v[82:85]
	v_mfma_f32_16x16x32_bf16 v[126:129], v[142:145], v[166:169], v[126:129]
	v_mfma_f32_16x16x32_bf16 v[114:117], v[158:161], v[166:169], v[114:117]
	v_mfma_f32_16x16x32_bf16 v[122:125], v[142:145], v[192:195], v[122:125]
	v_mfma_f32_16x16x32_bf16 v[118:121], v[158:161], v[192:195], v[118:121]
	v_mfma_f32_16x16x32_bf16 v[102:105], v[142:145], v[200:203], v[102:105]
	v_mfma_f32_16x16x32_bf16 v[98:101], v[158:161], v[200:203], v[98:101]
	v_mfma_f32_16x16x32_bf16 v[86:89], v[142:145], v[208:211], v[86:89]
	v_mfma_f32_16x16x32_bf16 v[82:85], v[158:161], v[208:211], v[82:85]
	s_setprio 0
	s_barrier
	s_add_i32 s26, s61, s38
	v_lshl_add_u64 v[220:221], v[220:221], 0, s[96:97]
	s_mov_b32 m0, s26
	ds_read_b128 v[162:165], v215 offset:49152
	ds_read_b128 v[166:169], v215 offset:50176
	ds_read_b128 v[170:173], v215 offset:51200
	ds_read_b128 v[192:195], v215 offset:52224
	ds_read_b128 v[196:199], v215 offset:53248
	ds_read_b128 v[200:203], v215 offset:54272
	ds_read_b128 v[204:207], v215 offset:55296
	ds_read_b128 v[208:211], v215 offset:56320
	global_load_lds_dwordx4 v[220:221], off
	s_add_i32 m0, s26, 0x2000
	s_add_u32 s26, s28, 0x160080
	v_lshl_add_u64 v[220:221], v[230:231], 0, s[96:97]
	s_addc_u32 s27, s29, 0
	s_add_i32 s28, s62, s38
	global_load_lds_dwordx4 v[220:221], off
	v_lshl_add_u64 v[220:221], s[26:27], 0, v[182:183]
	s_mov_b32 m0, s28
	s_nop 0
	global_load_lds_dwordx4 v[220:221], off
	v_lshl_add_u64 v[220:221], s[26:27], 0, v[178:179]
	s_add_i32 m0, s28, 0x2000
	s_nop 0
	global_load_lds_dwordx4 v[220:221], off
	v_lshl_add_u64 v[220:221], v[232:233], 0, s[96:97]
	s_mov_b32 m0, s54
	s_nop 0
	global_load_lds_dwordx4 v[220:221], off
	v_lshl_add_u64 v[220:221], v[234:235], 0, s[96:97]
	s_mov_b32 m0, s55
	s_nop 0
	global_load_lds_dwordx4 v[220:221], off
	s_waitcnt vmcnt(8) lgkmcnt(0)
	s_barrier
	s_setprio 1
	v_mfma_f32_16x16x32_bf16 v[62:65], v[66:69], v[162:165], v[62:65]
	v_mfma_f32_16x16x32_bf16 v[58:61], v[74:77], v[162:165], v[58:61]
	v_mfma_f32_16x16x32_bf16 v[46:49], v[66:69], v[170:173], v[46:49]
	v_mfma_f32_16x16x32_bf16 v[42:45], v[74:77], v[170:173], v[42:45]
	v_mfma_f32_16x16x32_bf16 v[30:33], v[66:69], v[196:199], v[30:33]
	v_mfma_f32_16x16x32_bf16 v[26:29], v[74:77], v[196:199], v[26:29]
	v_mfma_f32_16x16x32_bf16 v[14:17], v[66:69], v[204:207], v[14:17]
	v_mfma_f32_16x16x32_bf16 v[10:13], v[74:77], v[204:207], v[10:13]
	v_mfma_f32_16x16x32_bf16 v[62:65], v[70:73], v[166:169], v[62:65]
	v_mfma_f32_16x16x32_bf16 v[58:61], v[78:81], v[166:169], v[58:61]
	v_mfma_f32_16x16x32_bf16 v[46:49], v[70:73], v[192:195], v[46:49]
	v_mfma_f32_16x16x32_bf16 v[42:45], v[78:81], v[192:195], v[42:45]
	v_mfma_f32_16x16x32_bf16 v[30:33], v[70:73], v[200:203], v[30:33]
	v_mfma_f32_16x16x32_bf16 v[26:29], v[78:81], v[200:203], v[26:29]
	v_mfma_f32_16x16x32_bf16 v[14:17], v[70:73], v[208:211], v[14:17]
	v_mfma_f32_16x16x32_bf16 v[10:13], v[78:81], v[208:211], v[10:13]
	v_mfma_f32_16x16x32_bf16 v[54:57], v[130:133], v[162:165], v[54:57]
	v_mfma_f32_16x16x32_bf16 v[50:53], v[146:149], v[162:165], v[50:53]
	v_mfma_f32_16x16x32_bf16 v[38:41], v[130:133], v[170:173], v[38:41]
	v_mfma_f32_16x16x32_bf16 v[34:37], v[146:149], v[170:173], v[34:37]
	v_mfma_f32_16x16x32_bf16 v[22:25], v[130:133], v[196:199], v[22:25]
	v_mfma_f32_16x16x32_bf16 v[18:21], v[146:149], v[196:199], v[18:21]
	v_mfma_f32_16x16x32_bf16 v[6:9], v[130:133], v[204:207], v[6:9]
	v_mfma_f32_16x16x32_bf16 v[2:5], v[146:149], v[204:207], v[2:5]
	v_mfma_f32_16x16x32_bf16 v[54:57], v[142:145], v[166:169], v[54:57]
	v_mfma_f32_16x16x32_bf16 v[50:53], v[158:161], v[166:169], v[50:53]
	v_mfma_f32_16x16x32_bf16 v[38:41], v[142:145], v[192:195], v[38:41]
	v_mfma_f32_16x16x32_bf16 v[34:37], v[158:161], v[192:195], v[34:37]
	v_mfma_f32_16x16x32_bf16 v[22:25], v[142:145], v[200:203], v[22:25]
	v_mfma_f32_16x16x32_bf16 v[18:21], v[158:161], v[200:203], v[18:21]
	v_mfma_f32_16x16x32_bf16 v[6:9], v[142:145], v[208:211], v[6:9]
	v_mfma_f32_16x16x32_bf16 v[2:5], v[158:161], v[208:211], v[2:5]
	s_setprio 0
	s_barrier
	s_add_i32 s60, s60, 2
	s_add_u32 s19, s19, 0x100
	s_addc_u32 s21, s21, 0
	s_cmpk_gt_u32 s60, 0x55
	s_mov_b64 s[26:27], s[8:9]
	s_cbranch_scc0 .LBB0_905
	s_and_b64 vcc, exec, s[16:17]
	s_cbranch_vccz .LBB0_908
	s_barrier
